# diff attention pass-1 loop: K/V prefetch loads via scalar base + 6 loop-invariant 32-bit VGPR offsets (no per-load 64-bit VALU address math); on top of g4
# baseline (speedup 1.0000x reference)
; DI int otid() { int t = threadIdx.x; asm volatile("" : "+v"(t)); return t; }
; #define PROW() (P + (tokbase + qs0 + (otid() >> 6) * 32 + (otid() & 31)) * PW)
; DI void stage_q(const u16* qptr, char* lds) {
;   const int tid = otid(), lane = tid & 63, r = lane & 31, h = lane >> 5;
;   char* qlds = lds + 49152 + (tid >> 6) * 4096;
;   bf16x8 q[4];
; #pragma unroll
;   for (int s = 0; s < 4; ++s) q[s] = *(const bf16x8*)(qptr + 16 * s + 8 * h);
; #pragma unroll
;   for (int s = 0; s < 4; ++s) { const int ch = 2 * s + h; *(bf16x8*)(qlds + ch * 512 + ((r ^ ch) * 16)) = q[s]; }
; }
; DI void attn_item(const Params& p, int layer, int kind, int b, int hq, int qs0, char* lds) {
;   u16* P = (u16*)(p.ws + OFF_P);
;   const int tid = otid(), lane = tid & 63, wid = tid >> 6, r = lane & 31, h = lane >> 5;
;   const size_t tokbase = (size_t)b * SU;
;   const int sq = qs0 + wid * 32 + r;
;   const bool isctx = qs0 < LC;
;   if (kind == 2) {
;     const int hk = hq >> 1;
;     const float lam = ((const float*)(p.ws + OFF_SMALL + SM_LAM))[layer];
;     const float li = layer == 0 ? 0.2f : 0.35550906759096927f;
;     const int n1 = isctx ? 4 : 68;
;     ...
;     {
;       f32x16 o[4]; float ls;
;       stage_q(PROW() + C_DQ + (hq * 2 + 0) * 64, lds);
.LBB0_349:
	s_andn2_b64 vcc, exec, s[0:1]
	s_cbranch_vccnz .LBB0_395
	s_add_i32 s0, s66, 0xfffffef0
	s_waitcnt vmcnt(5)
	v_mov_b32_e32 v146, v190
	v_mov_b32_e32 v0, v190
	s_lshl_b32 s2, s0, 7
	global_load_dword v149, v65, s[38:39]
	s_and_b32 s2, s2, 0xf80
	v_ashrrev_i32_e32 v0, 1, v0
	s_add_i32 s50, s60, s2
	v_and_b32_e32 v0, 0xffffffe0, v0
	v_mov_b32_e32 v1, v190
	v_add_u32_e32 v0, s50, v0
	s_lshr_b32 s1, s0, 5
	v_and_or_b32 v2, v1, 31, v0
	v_mov_b64_e32 v[0:1], s[22:23]
	v_mov_b32_e32 v18, v190
	v_mad_i64_i32 v[0:1], s[2:3], v2, s89, v[0:1]
	s_lshl_b32 s26, s1, 7
	v_lshl_add_u64 v[0:1], s[26:27], 1, v[0:1]
	v_bfe_u32 v19, v18, 5, 1
	s_waitcnt vmcnt(5)
	v_lshlrev_b32_e32 v64, 4, v19
	v_lshl_add_u64 v[0:1], v[0:1], 0, v[64:65]
	s_mov_b64 s[2:3], 0x2200
	v_lshl_add_u64 v[14:15], v[0:1], 0, s[2:3]
	v_add_co_u32_e32 v0, vcc, s72, v0
	v_lshlrev_b32_e32 v20, 6, v18
	s_nop 0
	v_addc_co_u32_e32 v1, vcc, 0, v1, vcc
	global_load_dwordx4 v[2:5], v[0:1], off offset:512
	global_load_dwordx4 v[6:9], v[14:15], off offset:32
	global_load_dwordx4 v[10:13], v[14:15], off offset:64
	s_nop 0
	global_load_dwordx4 v[14:17], v[14:15], off offset:96
	v_lshrrev_b32_e32 v0, 5, v18
	v_and_b32_e32 v18, 31, v18
	s_lshl_b32 s51, s1, 6
	s_and_b32 s1, s26, 0x100
	v_bitop3_b32 v0, v0, v18, 1 bitop3:0x6c
	s_or_b32 s2, s1, 0x2600
	v_and_b32_e32 v20, 0xfffff000, v20
	v_lshlrev_b32_e32 v21, 9, v19
	v_or_b32_e32 v22, 2, v19
	v_bitop3_b32 v23, v19, v18, 2 bitop3:0x36
	v_or_b32_e32 v24, 4, v19
	v_bitop3_b32 v25, v19, v18, 4 bitop3:0x36
	v_or_b32_e32 v27, 6, v19
	v_bitop3_b32 v18, v19, v18, 6 bitop3:0x36
	v_lshlrev_b32_e32 v0, 4, v0
	s_add_u32 s2, s62, s2
	v_mov_b32_e32 v26, v190
	v_lshlrev_b32_e32 v19, 9, v22
	v_lshlrev_b32_e32 v22, 4, v23
	v_lshlrev_b32_e32 v23, 9, v24
	v_lshlrev_b32_e32 v24, 4, v25
	v_lshlrev_b32_e32 v25, 9, v27
	v_lshlrev_b32_e32 v18, 4, v18
	v_or3_b32 v0, v20, v21, v0
	s_addc_u32 s3, s63, 0
	s_or_b32 s1, s1, 0x2800
	v_or3_b32 v19, v20, v19, v22
	v_or3_b32 v21, v20, v23, v24
	v_or3_b32 v18, v20, v25, v18
	s_add_u32 s30, s62, s1
	v_mov_b32_e32 v1, v65
	s_addc_u32 s31, s63, 0
	s_lshl_b32 s0, s0, 2
	s_and_b32 s28, s0, 0x100
	s_mov_b32 s29, s27
	v_mov_b32_e32 v66, v65
	v_mov_b32_e32 v67, v65
	v_mov_b32_e32 v68, v65
	v_mov_b32_e32 v69, v65
	v_mov_b32_e32 v70, v65
	v_mov_b32_e32 v71, v65
	v_mov_b32_e32 v72, v65
	v_mov_b32_e32 v73, v65
	v_mov_b32_e32 v74, v65
	v_mov_b32_e32 v75, v65
	v_mov_b32_e32 v76, v65
	v_mov_b32_e32 v77, v65
	v_mov_b32_e32 v78, v65
	v_mov_b32_e32 v79, v65
	v_bfrev_b32_e32 v80, 1
	s_mov_b32 s67, 0
	v_mov_b32_e32 v185, 0
	v_mov_b32_e32 v165, 0
	v_mov_b32_e32 v81, v80
	v_mov_b32_e32 v82, v80
	v_mov_b32_e32 v83, v80
	v_mov_b32_e32 v84, v80
	s_waitcnt vmcnt(3)
	ds_write_b128 v0, v[2:5] offset:49152
	s_waitcnt vmcnt(2)
	ds_write_b128 v19, v[6:9] offset:49152
	s_waitcnt vmcnt(1)
	ds_write_b128 v21, v[10:13] offset:49152
	s_waitcnt vmcnt(0)
; DI int otid() { int t = threadIdx.x; asm volatile("" : "+v"(t)); return t; }
; DI f32x16 fzero() { f32x16 z; for (int i = 0; i < 16; ++i) z[i] = 0.f; return z; }
; template <int DV>
; DI void attn_core(const u16* __restrict__ P, size_t tokbase, int kcol, int vcol, int n1, int n2, int xs0,
;                   bool win, int tq, float m0, float l0, f32x16 (&o)[DV / 32], float& lsum, char* lds) {
;     ...
;   const int tid = otid(), lane = tid & 63, r = lane & 31, h = lane >> 5;
;   const char* qlds = lds + 49152 + (tid >> 6) * 4096;
;   bf16x8 qreg[4];
; #pragma unroll
;   for (int s = 0; s < 4; ++s) { const int ch = 2 * s + h; qreg[s] = *(const bf16x8*)(qlds + ch * 512 + ((r ^ ch) * 16)); }
;   u32x4 kA[2], vA[NVL], kB[2], vB[NVL];
;   const int ntiles = n1 + n2;
;   const int kkey = tid >> 3, kch = tid & 7;
;   const int vkey = tid >> VSH, vpc = tid & ((1 << VSH) - 1);
;   const int vstep = 256 >> VSH;
;   const bool autoinit = (l0 == 0.f);
;   float m = autoinit ? 0.f : m0, l = (h == 0) ? l0 : 0.f;
;   f32x16 negm;
; #pragma unroll
;   for (int reg = 0; reg < 16; ++reg) negm[reg] = -m;
; #pragma unroll
;   for (int b = 0; b < DV / 32; ++b) o[b] = fzero();
;   const int trofs = (4 * h + ((lane & 15) >> 2)) * 64 + ((lane >> 4) & 1) * 32 + (lane & 3) * 8;
;     ...
;   } else {
;     A_LOAD(kA, vA, 0);
;     A_STORE(kA, vA, 0);
;     __syncthreads();
	ds_write_b128 v18, v[14:17] offset:49152
	v_mov_b32_e32 v85, v80
	v_and_b32_e32 v29, 7, v26
	v_and_b32_e32 v0, 15, v26
	v_ashrrev_i32_e32 v27, 3, v26
	v_ashrrev_i32_e32 v28, 4, v26
	v_lshlrev_b32_e32 v64, 4, v29
	v_lshlrev_b32_e32 v0, 4, v0
	v_add_u32_e32 v30, 32, v27
	v_add_u32_e32 v8, 16, v28
	v_add_u32_e32 v20, 32, v28
	v_lshl_add_u64 v[2:3], s[2:3], 0, v[64:65]
	v_lshl_add_u64 v[18:19], s[30:31], 0, v[0:1]
	v_add_u32_e32 v22, 48, v28
	v_mad_i64_i32 v[4:5], s[2:3], v27, s89, v[2:3]
	v_mad_i64_i32 v[6:7], s[2:3], v30, s89, v[2:3]
	v_mad_i64_i32 v[10:11], s[2:3], v28, s89, v[18:19]
	v_mad_i64_i32 v[14:15], s[2:3], v8, s89, v[18:19]
	v_mad_i64_i32 v[20:21], s[2:3], v20, s89, v[18:19]
	v_mad_i64_i32 v[22:23], s[2:3], v22, s89, v[18:19]
	global_load_dwordx4 v[2:5], v[4:5], off
	s_nop 0
	global_load_dwordx4 v[6:9], v[6:7], off
	s_nop 0
	global_load_dwordx4 v[10:13], v[10:11], off
	s_nop 0
	global_load_dwordx4 v[14:17], v[14:15], off
	s_nop 0
	global_load_dwordx4 v[18:21], v[20:21], off
	s_nop 0
	global_load_dwordx4 v[22:25], v[22:23], off
	v_and_b32_e32 v31, 31, v26
	v_lshrrev_b32_e32 v32, 5, v26
	v_bfe_u32 v33, v26, 5, 1
	v_lshlrev_b32_e32 v35, 4, v26
	v_lshlrev_b32_e32 v34, 6, v26
	v_lshlrev_b32_e32 v38, 10, v26
	v_bitop3_b32 v32, v32, v31, 1 bitop3:0x6c
	v_bitop3_b32 v45, v33, v31, 6 bitop3:0x36
	v_and_b32_e32 v46, 0xc0, v35
	v_bitop3_b32 v47, v27, v26, 7 bitop3:0x78
	v_lshlrev_b32_e32 v36, 1, v26
	v_lshlrev_b32_e32 v37, 3, v26
	v_and_b32_e32 v34, 0xfffff000, v34
	v_lshlrev_b32_e32 v39, 9, v33
	v_or_b32_e32 v40, 2, v33
	v_bitop3_b32 v41, v33, v31, 2 bitop3:0x36
	v_or_b32_e32 v42, 4, v33
	v_bitop3_b32 v43, v33, v31, 4 bitop3:0x36
	v_or_b32_e32 v44, 6, v33
	v_lshlrev_b32_e32 v29, 10, v29
	v_and_b32_e32 v38, 0x3000, v38
	v_and_b32_e32 v147, 48, v35
	v_or_b32_e32 v35, 32, v31
	v_bitop3_b32 v31, v31, v33, 32 bitop3:0x36
	v_lshlrev_b32_e32 v150, 4, v32
	v_lshlrev_b32_e32 v153, 4, v45
	v_lshl_or_b32 v45, v33, 8, v46
	v_lshlrev_b32_e32 v46, 4, v47
	v_bitop3_b32 v26, v30, v26, 7 bitop3:0x78
	v_lshlrev_b32_e32 v148, 10, v33
	v_lshlrev_b32_e32 v32, 9, v40
	v_lshlrev_b32_e32 v151, 4, v41
	v_lshlrev_b32_e32 v41, 9, v42
	v_lshlrev_b32_e32 v152, 4, v43
	v_lshlrev_b32_e32 v43, 9, v44
	v_lshl_add_u32 v154, v28, 6, v38
	v_lshlrev_b32_e32 v30, 4, v31
	v_bitop3_b32 v31, v33, v35, 2 bitop3:0x36
	v_bitop3_b32 v38, v33, v35, 4 bitop3:0x36
	v_bitop3_b32 v33, v33, v35, 6 bitop3:0x36
	v_or3_b32 v35, v34, v39, v150
	v_add_u32_e32 v158, v29, v46
	v_lshlrev_b32_e32 v26, 4, v26
	v_lshlrev_b32_e32 v155, 10, v40
	v_or3_b32 v32, v34, v32, v151
	v_or3_b32 v39, v34, v41, v152
	v_or3_b32 v34, v34, v43, v153
	v_or_b32_e32 v40, v154, v147
	ds_read_b128 v[112:115], v35 offset:49152
	ds_read_b128 v[116:119], v32 offset:49152
	ds_read_b128 v[120:123], v39 offset:49152
	ds_read_b128 v[124:127], v34 offset:49152
	v_add_u32_e32 v160, v29, v26
	s_waitcnt vmcnt(5)
	ds_write_b128 v158, v[2:5]
	s_waitcnt vmcnt(4)
	ds_write_b128 v160, v[6:9]
	s_waitcnt vmcnt(3)
	ds_write_b128 v40, v[10:13] offset:8192
	s_waitcnt vmcnt(2)
	ds_write_b128 v40, v[14:17] offset:9216
	s_waitcnt vmcnt(1)
	ds_write_b128 v40, v[18:21] offset:10240
	s_waitcnt vmcnt(0)
	ds_write_b128 v40, v[22:25] offset:11264
	v_mov_b64_e32 v[2:3], s[28:29]
	v_mad_i64_i32 v[2:3], s[0:1], v27, s89, v[2:3]
	v_lshl_add_u64 v[2:3], v[2:3], 0, v[64:65]
	v_lshl_add_u64 v[140:141], s[48:49], 0, v[2:3]
	v_mov_b64_e32 v[2:3], s[28:29]
	v_and_b32_e32 v36, 32, v36
	v_and_b32_e32 v37, 24, v37
	v_mad_i64_i32 v[2:3], s[0:1], v28, s89, v[2:3]
	v_lshlrev_b32_e32 v156, 10, v42
	v_lshlrev_b32_e32 v157, 10, v44
	v_or3_b32 v159, v45, v36, v37
	v_lshlrev_b32_e32 v31, 4, v31
	v_lshlrev_b32_e32 v36, 4, v38
	v_lshlrev_b32_e32 v33, 4, v33
	v_lshl_add_u64 v[0:1], v[2:3], 0, v[0:1]
	v_mov_b32_e32 v64, v65
	v_lshl_add_u64 v[142:143], s[48:49], 0, v[0:1]
	s_add_u32 s92, s48, s28
	s_addc_u32 s93, s49, s29
	s_sub_u32 s92, s92, 0x100000
	s_subb_u32 s93, s93, 0
	v_subrev_u32_e32 v174, s92, v140
	v_subrev_u32_e32 v176, s92, v142
	v_add_u32_e32 v175, 0x117e00, v174
	v_add_u32_e32 v174, 0xbb600, v174
	v_add_u32_e32 v177, 0xe9c00, v176
	v_add_u32_e32 v178, 0x118000, v176
	v_add_u32_e32 v179, 0x146400, v176
	v_add_u32_e32 v176, 0xbb800, v176
	v_add_u32_e32 v161, v148, v30
	v_add_u32_e32 v162, v155, v31
	v_add_u32_e32 v163, v156, v36
	v_add_u32_e32 v164, v157, v33
	v_mov_b64_e32 v[0:1], v[64:65]
	v_mov_b64_e32 v[16:17], v[64:65]
	v_mov_b64_e32 v[32:33], v[64:65]
	v_mov_b64_e32 v[48:49], v[64:65]
	s_mov_b64 s[2:3], 0
	v_mov_b64_e32 v[2:3], v[66:67]
	v_mov_b64_e32 v[4:5], v[68:69]
	v_mov_b64_e32 v[6:7], v[70:71]
	v_mov_b64_e32 v[8:9], v[72:73]
	v_mov_b64_e32 v[10:11], v[74:75]
	v_mov_b64_e32 v[12:13], v[76:77]
	v_mov_b64_e32 v[14:15], v[78:79]
	v_mov_b64_e32 v[18:19], v[66:67]
	v_mov_b64_e32 v[20:21], v[68:69]
	v_mov_b64_e32 v[22:23], v[70:71]
	v_mov_b64_e32 v[24:25], v[72:73]
	v_mov_b64_e32 v[26:27], v[74:75]
	v_mov_b64_e32 v[28:29], v[76:77]
	v_mov_b64_e32 v[30:31], v[78:79]
	v_mov_b64_e32 v[34:35], v[66:67]
	v_mov_b64_e32 v[36:37], v[68:69]
	v_mov_b64_e32 v[38:39], v[70:71]
	v_mov_b64_e32 v[40:41], v[72:73]
	v_mov_b64_e32 v[42:43], v[74:75]
	v_mov_b64_e32 v[44:45], v[76:77]
	v_mov_b64_e32 v[46:47], v[78:79]
	v_mov_b64_e32 v[50:51], v[66:67]
	v_mov_b64_e32 v[52:53], v[68:69]
	v_mov_b64_e32 v[54:55], v[70:71]
	v_mov_b64_e32 v[56:57], v[72:73]
	v_mov_b64_e32 v[58:59], v[74:75]
	v_mov_b64_e32 v[60:61], v[76:77]
	v_mov_b64_e32 v[62:63], v[78:79]
	v_mov_b32_e32 v86, v80
	v_mov_b32_e32 v87, v80
	v_mov_b32_e32 v88, v80
	v_mov_b32_e32 v89, v80
	v_mov_b32_e32 v90, v80
	v_mov_b32_e32 v91, v80
	v_mov_b32_e32 v92, v80
	v_mov_b32_e32 v93, v80
	v_mov_b32_e32 v94, v80
	v_mov_b32_e32 v95, v80
	s_waitcnt lgkmcnt(0)
	s_barrier
	s_branch .LBB0_352

; #define MFMA(a, b, c) __builtin_amdgcn_mfma_f32_32x32x16_bf16((a), (b), (c), 0, 0, 0)
; DI int crow(int reg, int h) { return (reg & 3) + 8 * (reg >> 2) + 4 * h; }
; DI float mx2(float a, float b) { return __builtin_elementwise_maximum(a, b); }
; DI float hmax(float v) { auto rr = __builtin_amdgcn_permlane32_swap(__float_as_uint(v), __float_as_uint(v), false, false); return mx2(__uint_as_float(rr[0]), __uint_as_float(rr[1])); }
; template <int DV>
; DI void attn_core(const u16* __restrict__ P, size_t tokbase, int kcol, int vcol, int n1, int n2, int xs0,
;                   bool win, int tq, float m0, float l0, f32x16 (&o)[DV / 32], float& lsum, char* lds) {
;     ...
;     for (int ks = 0; ks < 2; ++ks) {
;       f32x16 pt = negm;
; #pragma unroll
;       for (int s = 0; s < 4; ++s) {
;         const int ch = 2 * s + h, key = 32 * ks + r;
;         const bf16x8 kf = *(const bf16x8*)(base + ch * 1024 + ((key ^ ch) * 16));
;         const bf16x8 qf = qreg[s];
;         pt = MFMA(kf, qf, pt);
;       }
;       if (domask) {
; #pragma unroll
;         for (int reg = 0; reg < 16; ++reg) {
;           const int d = tq - (kt0 + 32 * ks + crow(reg, h));
;           if (d > 128 || d < -128) pt[reg] = -1e30f;
;         }
;       }
;       float mloc = mx2(pt[0], pt[1]);
; #pragma unroll
;       for (int reg = 2; reg < 16; reg += 2) mloc = mx2(mx2(mloc, pt[reg]), pt[reg + 1]);
;       mloc = hmax(mloc);
;       const bool first = autoinit && it == 0 && ks == 0;
;       if (first || __builtin_amdgcn_ballot_w64(mloc > THR) != 0) {
;     ...
;     for (int it = 0; it < ntiles; it += 2) {
;       A_LOAD(kA, vA, it + 1);
;       compute(lds, it);
.LBB0_352:
	s_add_u32 s94, s92, s2
	s_addc_u32 s95, s93, s3
	s_waitcnt vmcnt(5)
	s_mov_b32 s0, 0x117000
	s_nop 0
	s_waitcnt vmcnt(4)
	s_nop 0
	s_waitcnt vmcnt(3)
	global_load_dwordx4 v[66:69], v174, s[94:95]
	global_load_dwordx4 v[74:77], v176, s[94:95]
	global_load_dwordx4 v[128:131], v177, s[94:95]
	global_load_dwordx4 v[70:73], v175, s[94:95]
	global_load_dwordx4 v[132:135], v178, s[94:95]
	v_add_u32_e32 v167, v148, v150
	global_load_dwordx4 v[136:139], v179, s[94:95]
	ds_read_b128 v[168:171], v167
	v_add_u32_e32 v173, v155, v151
	s_waitcnt lgkmcnt(0)
	v_mfma_f32_32x32x16_bf16 v[96:111], v[168:171], v[112:115], v[80:95]
	ds_read_b128 v[168:171], v173
	v_add_u32_e32 v181, v156, v152
	v_add_u32_e32 v184, v157, v153
	s_cmp_lg_u32 s2, 0
	s_waitcnt lgkmcnt(0)
	v_mfma_f32_32x32x16_bf16 v[96:111], v[168:171], v[116:119], v[96:111]
	ds_read_b128 v[168:171], v181
	s_waitcnt lgkmcnt(0)
	v_mfma_f32_32x32x16_bf16 v[96:111], v[168:171], v[120:123], v[96:111]
	ds_read_b128 v[168:171], v184
	s_waitcnt lgkmcnt(0)
	v_mfma_f32_32x32x16_bf16 v[96:111], v[168:171], v[124:127], v[96:111]
	s_nop 11
	v_maximum3_f32 v64, v96, v97, v97
	v_maximum3_f32 v64, v64, v98, v99
	v_maximum3_f32 v64, v64, v100, v101
	v_maximum3_f32 v64, v64, v102, v103
	v_maximum3_f32 v64, v64, v104, v105
	v_maximum3_f32 v64, v64, v106, v107
	v_maximum3_f32 v64, v64, v108, v109
	v_maximum3_f32 v64, v64, v110, v111
	v_mov_b32_e32 v166, v64
	s_nop 1
	v_permlane32_swap_b32_e32 v64, v166
	v_maximum3_f32 v166, v64, v166, v166
	s_cbranch_scc0 .LBB0_368
	v_cmp_lt_f32_e32 vcc, s80, v166
	s_mov_b64 s[36:37], 0
	s_mov_b64 s[0:1], 0
	s_cbranch_vccz .LBB0_355
	v_max_f32_e32 v64, v166, v166
	v_max_f32_e32 v64, 0, v64
	s_mov_b64 s[0:1], -1

; #define MFMA(a, b, c) __builtin_amdgcn_mfma_f32_32x32x16_bf16((a), (b), (c), 0, 0, 0)
; DI s16x4 vtr(const char* p) { return __builtin_bit_cast(s16x4, __builtin_amdgcn_ds_read_tr16_b64_v4i16((__attribute__((address_space(3))) v4i16_t*)(lds_cptr)p)); }
; DI bf16x8 cat8(s16x4 lo, s16x4 hi) { return __builtin_shufflevector(lo, hi, 0, 1, 2, 3, 4, 5, 6, 7); }
; DI float fexp2(float x) { return __builtin_amdgcn_exp2f(x); }
; template <int DV>
; DI void attn_core(const u16* __restrict__ P, size_t tokbase, int kcol, int vcol, int n1, int n2, int xs0,
;                   bool win, int tq, float m0, float l0, f32x16 (&o)[DV / 32], float& lsum, char* lds) {
;     ...
;       if (first || __builtin_amdgcn_ballot_w64(mloc > THR) != 0) {
;         const float d = first ? mloc : fmaxf(mloc, 0.f);
;         const float alpha = fexp2(-d);
;         m += d; l *= alpha;
; #pragma unroll
;         for (int reg = 0; reg < 16; ++reg) { negm[reg] = -m; pt[reg] -= d; }
; #pragma unroll
;         for (int b = 0; b < DV / 32; ++b)
; #pragma unroll
;           for (int reg = 0; reg < 16; ++reg) o[b][reg] *= alpha;
;       }
;       float la = 0.f;
; #pragma unroll
;       for (int reg = 0; reg < 16; ++reg) { const float e = fexp2(pt[reg]); pt[reg] = e; la += e; }
;       l += la;
; #pragma unroll
;       for (int s2 = 0; s2 < 2; ++s2) {
;         const bf16x8 pb = pack8(pt, s2);
;         const int s16 = 2 * ks + s2;
; #pragma unroll
;         for (int b = 0; b < DV / 32; ++b) {
;           const char* va = base + KB + b * 4096 + s16 * 1024 + trofs;
;           const bf16x8 vf = cat8(vtr(va), vtr(va + 512));
;           o[b] = MFMA(vf, pb, o[b]);
;         }
;       }
.LBB0_357:
	s_andn2_b64 vcc, exec, s[0:1]
	s_cbranch_vccnz .LBB0_359
	v_exp_f32_e64 v82, -v64
	v_add_f32_e32 v165, v165, v64
	v_xor_b32_e32 v80, 0x80000000, v165
	v_pk_add_f32 v[96:97], v[96:97], v[64:65] op_sel_hi:[1,0] neg_lo:[0,1] neg_hi:[0,1]
	v_mul_f32_e32 v185, v185, v82
	v_pk_add_f32 v[98:99], v[98:99], v[64:65] op_sel_hi:[1,0] neg_lo:[0,1] neg_hi:[0,1]
	v_pk_add_f32 v[100:101], v[100:101], v[64:65] op_sel_hi:[1,0] neg_lo:[0,1] neg_hi:[0,1]
	v_pk_add_f32 v[102:103], v[102:103], v[64:65] op_sel_hi:[1,0] neg_lo:[0,1] neg_hi:[0,1]
	v_pk_add_f32 v[104:105], v[104:105], v[64:65] op_sel_hi:[1,0] neg_lo:[0,1] neg_hi:[0,1]
	v_pk_add_f32 v[106:107], v[106:107], v[64:65] op_sel_hi:[1,0] neg_lo:[0,1] neg_hi:[0,1]
	v_pk_add_f32 v[108:109], v[108:109], v[64:65] op_sel_hi:[1,0] neg_lo:[0,1] neg_hi:[0,1]
	v_pk_add_f32 v[110:111], v[110:111], v[64:65] op_sel_hi:[1,0] neg_lo:[0,1] neg_hi:[0,1]
	v_pk_mul_f32 v[62:63], v[62:63], v[82:83] op_sel_hi:[1,0]
	v_pk_mul_f32 v[60:61], v[60:61], v[82:83] op_sel_hi:[1,0]
	v_pk_mul_f32 v[58:59], v[58:59], v[82:83] op_sel_hi:[1,0]
	v_pk_mul_f32 v[56:57], v[56:57], v[82:83] op_sel_hi:[1,0]
	v_pk_mul_f32 v[54:55], v[54:55], v[82:83] op_sel_hi:[1,0]
	v_pk_mul_f32 v[52:53], v[52:53], v[82:83] op_sel_hi:[1,0]
	v_pk_mul_f32 v[50:51], v[50:51], v[82:83] op_sel_hi:[1,0]
	v_pk_mul_f32 v[48:49], v[48:49], v[82:83] op_sel_hi:[1,0]
	v_pk_mul_f32 v[46:47], v[46:47], v[82:83] op_sel_hi:[1,0]
	v_pk_mul_f32 v[44:45], v[44:45], v[82:83] op_sel_hi:[1,0]
	v_pk_mul_f32 v[42:43], v[42:43], v[82:83] op_sel_hi:[1,0]
	v_pk_mul_f32 v[40:41], v[40:41], v[82:83] op_sel_hi:[1,0]
	v_pk_mul_f32 v[38:39], v[38:39], v[82:83] op_sel_hi:[1,0]
	v_pk_mul_f32 v[36:37], v[36:37], v[82:83] op_sel_hi:[1,0]
	v_pk_mul_f32 v[34:35], v[34:35], v[82:83] op_sel_hi:[1,0]
	v_pk_mul_f32 v[32:33], v[32:33], v[82:83] op_sel_hi:[1,0]
	v_pk_mul_f32 v[30:31], v[30:31], v[82:83] op_sel_hi:[1,0]
	v_pk_mul_f32 v[28:29], v[28:29], v[82:83] op_sel_hi:[1,0]
	v_pk_mul_f32 v[26:27], v[26:27], v[82:83] op_sel_hi:[1,0]
	v_pk_mul_f32 v[24:25], v[24:25], v[82:83] op_sel_hi:[1,0]
	v_pk_mul_f32 v[22:23], v[22:23], v[82:83] op_sel_hi:[1,0]
	v_pk_mul_f32 v[20:21], v[20:21], v[82:83] op_sel_hi:[1,0]
	v_pk_mul_f32 v[18:19], v[18:19], v[82:83] op_sel_hi:[1,0]
	v_pk_mul_f32 v[16:17], v[16:17], v[82:83] op_sel_hi:[1,0]
	v_pk_mul_f32 v[14:15], v[14:15], v[82:83] op_sel_hi:[1,0]
	v_pk_mul_f32 v[12:13], v[12:13], v[82:83] op_sel_hi:[1,0]
	v_pk_mul_f32 v[10:11], v[10:11], v[82:83] op_sel_hi:[1,0]
	v_pk_mul_f32 v[8:9], v[8:9], v[82:83] op_sel_hi:[1,0]
	v_pk_mul_f32 v[6:7], v[6:7], v[82:83] op_sel_hi:[1,0]
	v_pk_mul_f32 v[4:5], v[4:5], v[82:83] op_sel_hi:[1,0]
	v_pk_mul_f32 v[2:3], v[2:3], v[82:83] op_sel_hi:[1,0]
	v_pk_mul_f32 v[0:1], v[0:1], v[82:83] op_sel_hi:[1,0]
	v_mov_b32_e32 v81, v80
	v_mov_b32_e32 v82, v80
	v_mov_b32_e32 v83, v80
	v_mov_b32_e32 v84, v80
	v_mov_b32_e32 v85, v80
	v_mov_b32_e32 v86, v80
	v_mov_b32_e32 v87, v80
	v_mov_b32_e32 v88, v80
	v_mov_b32_e32 v89, v80
	v_mov_b32_e32 v90, v80
	v_mov_b32_e32 v91, v80
	v_mov_b32_e32 v92, v80
	v_mov_b32_e32 v93, v80
	v_mov_b32_e32 v94, v80
	v_mov_b32_e32 v95, v80
	v_mov_b32_e32 v64, v80
	v_mov_b32_e32 v166, v80
	v_mov_b32_e32 v168, v80
	v_mov_b32_e32 v169, v80
	v_mov_b32_e32 v170, v80
	v_mov_b32_e32 v171, v80
	v_mov_b32_e32 v172, v80
	v_mov_b32_e32 v180, v80
	v_mov_b32_e32 v182, v80
	v_mov_b32_e32 v183, v80
	s_branch .LBB0_360
.LBB0_359:
.LBB0_360:
	v_exp_f32_e32 v96, v96
	v_exp_f32_e32 v97, v97
	v_exp_f32_e32 v98, v98
	v_exp_f32_e32 v99, v99
	v_add_f32_e32 v186, 0, v96
	v_exp_f32_e32 v100, v100
	v_add_f32_e32 v186, v97, v186
	v_exp_f32_e32 v101, v101
	v_add_f32_e32 v186, v98, v186
	v_exp_f32_e32 v102, v102
	v_add_f32_e32 v186, v99, v186
	v_exp_f32_e32 v103, v103
	v_add_f32_e32 v186, v100, v186
	v_add_f32_e32 v186, v101, v186
	v_add_f32_e32 v186, v102, v186
	v_add_f32_e32 v186, v103, v186
	v_cvt_pk_bf16_f32 v96, v96, v97
	v_cvt_pk_bf16_f32 v97, v98, v99
	v_cvt_pk_bf16_f32 v98, v100, v101
	v_cvt_pk_bf16_f32 v99, v102, v103
	ds_read_b64_tr_b16 v[100:101], v159 offset:8192
	ds_read_b64_tr_b16 v[102:103], v159 offset:8704
	s_waitcnt lgkmcnt(0)
	v_mfma_f32_32x32x16_bf16 v[48:63], v[100:103], v[96:99], v[48:63]
	ds_read_b64_tr_b16 v[100:101], v159 offset:12288
	ds_read_b64_tr_b16 v[102:103], v159 offset:12800
	v_exp_f32_e32 v104, v104
	v_exp_f32_e32 v105, v105
	v_exp_f32_e32 v106, v106
	v_exp_f32_e32 v107, v107
	v_exp_f32_e32 v108, v108
	v_exp_f32_e32 v109, v109
	s_waitcnt lgkmcnt(0)
	v_mfma_f32_32x32x16_bf16 v[32:47], v[100:103], v[96:99], v[32:47]
	ds_read_b64_tr_b16 v[100:101], v159 offset:16384
	ds_read_b64_tr_b16 v[102:103], v159 offset:16896
	v_exp_f32_e32 v110, v110
	v_exp_f32_e32 v111, v111
	v_add_f32_e32 v186, v104, v186
	v_add_f32_e32 v186, v105, v186
	v_add_f32_e32 v186, v106, v186
	v_add_f32_e32 v186, v107, v186
	s_waitcnt lgkmcnt(0)
	v_mfma_f32_32x32x16_bf16 v[16:31], v[100:103], v[96:99], v[16:31]
	ds_read_b64_tr_b16 v[100:101], v159 offset:20480
	ds_read_b64_tr_b16 v[102:103], v159 offset:20992
	v_add_f32_e32 v186, v108, v186
	v_add_f32_e32 v186, v109, v186
	v_add_f32_e32 v186, v110, v186
	v_add_f32_e32 v186, v111, v186
	v_add_f32_e32 v186, v185, v186
	s_waitcnt lgkmcnt(0)
	v_mfma_f32_32x32x16_bf16 v[0:15], v[100:103], v[96:99], v[0:15]
	ds_read_b64_tr_b16 v[100:101], v159 offset:9216
	ds_read_b64_tr_b16 v[102:103], v159 offset:9728
	v_cvt_pk_bf16_f32 v96, v104, v105
	v_cvt_pk_bf16_f32 v97, v106, v107
	v_cvt_pk_bf16_f32 v98, v108, v109
	v_cvt_pk_bf16_f32 v99, v110, v111
	s_waitcnt lgkmcnt(0)
	s_nop 0
	v_mfma_f32_32x32x16_bf16 v[48:63], v[100:103], v[96:99], v[48:63]
	ds_read_b64_tr_b16 v[100:101], v159 offset:13312
	ds_read_b64_tr_b16 v[102:103], v159 offset:13824
	s_waitcnt lgkmcnt(0)
; #define MFMA(a, b, c) __builtin_amdgcn_mfma_f32_32x32x16_bf16((a), (b), (c), 0, 0, 0)
; DI int crow(int reg, int h) { return (reg & 3) + 8 * (reg >> 2) + 4 * h; }
; DI s16x4 vtr(const char* p) { return __builtin_bit_cast(s16x4, __builtin_amdgcn_ds_read_tr16_b64_v4i16((__attribute__((address_space(3))) v4i16_t*)(lds_cptr)p)); }
; DI bf16x8 cat8(s16x4 lo, s16x4 hi) { return __builtin_shufflevector(lo, hi, 0, 1, 2, 3, 4, 5, 6, 7); }
; DI float fexp2(float x) { return __builtin_amdgcn_exp2f(x); }
; template <int DV>
; DI void attn_core(const u16* __restrict__ P, size_t tokbase, int kcol, int vcol, int n1, int n2, int xs0,
;                   bool win, int tq, float m0, float l0, f32x16 (&o)[DV / 32], float& lsum, char* lds) {
;     ...
;     for (int ks = 0; ks < 2; ++ks) {
;       f32x16 pt = negm;
; #pragma unroll
;       for (int s = 0; s < 4; ++s) {
;         const int ch = 2 * s + h, key = 32 * ks + r;
;         const bf16x8 kf = *(const bf16x8*)(base + ch * 1024 + ((key ^ ch) * 16));
;         const bf16x8 qf = qreg[s];
;         pt = MFMA(kf, qf, pt);
;       }
;       if (domask) {
; #pragma unroll
;         for (int reg = 0; reg < 16; ++reg) {
;           const int d = tq - (kt0 + 32 * ks + crow(reg, h));
;           if (d > 128 || d < -128) pt[reg] = -1e30f;
;         }
;       }
;       float mloc = mx2(pt[0], pt[1]);
; #pragma unroll
;       for (int reg = 2; reg < 16; reg += 2) mloc = mx2(mx2(mloc, pt[reg]), pt[reg + 1]);
;       mloc = hmax(mloc);
;       const bool first = autoinit && it == 0 && ks == 0;
;       if (first || __builtin_amdgcn_ballot_w64(mloc > THR) != 0) {
;         const float d = first ? mloc : fmaxf(mloc, 0.f);
;         const float alpha = fexp2(-d);
;         m += d; l *= alpha;
; #pragma unroll
;         for (int reg = 0; reg < 16; ++reg) { negm[reg] = -m; pt[reg] -= d; }
; #pragma unroll
;         for (int b = 0; b < DV / 32; ++b)
; #pragma unroll
;           for (int reg = 0; reg < 16; ++reg) o[b][reg] *= alpha;
;       }
;     ...
;       for (int s2 = 0; s2 < 2; ++s2) {
;         const bf16x8 pb = pack8(pt, s2);
;         const int s16 = 2 * ks + s2;
; #pragma unroll
;         for (int b = 0; b < DV / 32; ++b) {
;           const char* va = base + KB + b * 4096 + s16 * 1024 + trofs;
;           const bf16x8 vf = cat8(vtr(va), vtr(va + 512));
;           o[b] = MFMA(vf, pb, o[b]);
;         }
;       }
	v_mfma_f32_32x32x16_bf16 v[32:47], v[100:103], v[96:99], v[32:47]
	ds_read_b64_tr_b16 v[100:101], v159 offset:17408
	ds_read_b64_tr_b16 v[102:103], v159 offset:17920
	s_waitcnt lgkmcnt(0)
	v_mfma_f32_32x32x16_bf16 v[16:31], v[100:103], v[96:99], v[16:31]
	ds_read_b64_tr_b16 v[100:101], v159 offset:21504
	ds_read_b64_tr_b16 v[102:103], v159 offset:22016
	ds_read_b128 v[206:209], v161
	s_waitcnt lgkmcnt(1)
	v_mfma_f32_32x32x16_bf16 v[0:15], v[100:103], v[96:99], v[0:15]
	s_waitcnt lgkmcnt(0)
	v_mfma_f32_32x32x16_bf16 v[96:111], v[206:209], v[112:115], v[80:95]
	ds_read_b128 v[206:209], v162
	s_waitcnt lgkmcnt(0)
	v_mfma_f32_32x32x16_bf16 v[96:111], v[206:209], v[116:119], v[96:111]
	ds_read_b128 v[206:209], v163
	s_waitcnt lgkmcnt(0)
	v_mfma_f32_32x32x16_bf16 v[96:111], v[206:209], v[120:123], v[96:111]
	ds_read_b128 v[206:209], v164
	s_waitcnt lgkmcnt(0)
	v_mfma_f32_32x32x16_bf16 v[96:111], v[206:209], v[124:127], v[96:111]
	s_nop 11
	v_maximum3_f32 v185, v96, v97, v97
	v_maximum3_f32 v185, v185, v98, v99
	v_maximum3_f32 v185, v185, v100, v101
	v_maximum3_f32 v185, v185, v102, v103
	v_maximum3_f32 v185, v185, v104, v105
	v_maximum3_f32 v185, v185, v106, v107
	v_maximum3_f32 v185, v185, v108, v109
	v_maximum3_f32 v185, v185, v110, v111
	v_mov_b32_e32 v187, v185
	s_nop 1
	v_permlane32_swap_b32_e32 v185, v187
	v_maximum3_f32 v185, v185, v187, v187
	v_cmp_lt_f32_e32 vcc, s80, v185
	s_cbranch_vccz .LBB0_362
	v_max_f32_e32 v64, v185, v185
	v_max_f32_e32 v64, 0, v64
	v_exp_f32_e64 v82, -v64
	v_add_f32_e32 v165, v165, v64
	v_xor_b32_e32 v80, 0x80000000, v165
	v_pk_add_f32 v[96:97], v[96:97], v[64:65] op_sel_hi:[1,0] neg_lo:[0,1] neg_hi:[0,1]
	v_mul_f32_e32 v186, v186, v82
	v_pk_add_f32 v[98:99], v[98:99], v[64:65] op_sel_hi:[1,0] neg_lo:[0,1] neg_hi:[0,1]
	v_pk_add_f32 v[100:101], v[100:101], v[64:65] op_sel_hi:[1,0] neg_lo:[0,1] neg_hi:[0,1]
	v_pk_add_f32 v[102:103], v[102:103], v[64:65] op_sel_hi:[1,0] neg_lo:[0,1] neg_hi:[0,1]
	v_pk_add_f32 v[104:105], v[104:105], v[64:65] op_sel_hi:[1,0] neg_lo:[0,1] neg_hi:[0,1]
	v_pk_add_f32 v[106:107], v[106:107], v[64:65] op_sel_hi:[1,0] neg_lo:[0,1] neg_hi:[0,1]
	v_pk_add_f32 v[108:109], v[108:109], v[64:65] op_sel_hi:[1,0] neg_lo:[0,1] neg_hi:[0,1]
	v_pk_add_f32 v[110:111], v[110:111], v[64:65] op_sel_hi:[1,0] neg_lo:[0,1] neg_hi:[0,1]
	v_pk_mul_f32 v[62:63], v[62:63], v[82:83] op_sel_hi:[1,0]
	v_pk_mul_f32 v[60:61], v[60:61], v[82:83] op_sel_hi:[1,0]
	v_pk_mul_f32 v[58:59], v[58:59], v[82:83] op_sel_hi:[1,0]
	v_pk_mul_f32 v[56:57], v[56:57], v[82:83] op_sel_hi:[1,0]
	v_pk_mul_f32 v[54:55], v[54:55], v[82:83] op_sel_hi:[1,0]
	v_pk_mul_f32 v[52:53], v[52:53], v[82:83] op_sel_hi:[1,0]
	v_pk_mul_f32 v[50:51], v[50:51], v[82:83] op_sel_hi:[1,0]
	v_pk_mul_f32 v[48:49], v[48:49], v[82:83] op_sel_hi:[1,0]
	v_pk_mul_f32 v[46:47], v[46:47], v[82:83] op_sel_hi:[1,0]
	v_pk_mul_f32 v[44:45], v[44:45], v[82:83] op_sel_hi:[1,0]
	v_pk_mul_f32 v[42:43], v[42:43], v[82:83] op_sel_hi:[1,0]
	v_pk_mul_f32 v[40:41], v[40:41], v[82:83] op_sel_hi:[1,0]
	v_pk_mul_f32 v[38:39], v[38:39], v[82:83] op_sel_hi:[1,0]
	v_pk_mul_f32 v[36:37], v[36:37], v[82:83] op_sel_hi:[1,0]
	v_pk_mul_f32 v[34:35], v[34:35], v[82:83] op_sel_hi:[1,0]
	v_pk_mul_f32 v[32:33], v[32:33], v[82:83] op_sel_hi:[1,0]
	v_pk_mul_f32 v[30:31], v[30:31], v[82:83] op_sel_hi:[1,0]
	v_pk_mul_f32 v[28:29], v[28:29], v[82:83] op_sel_hi:[1,0]
	v_pk_mul_f32 v[26:27], v[26:27], v[82:83] op_sel_hi:[1,0]
	v_pk_mul_f32 v[24:25], v[24:25], v[82:83] op_sel_hi:[1,0]
	v_pk_mul_f32 v[22:23], v[22:23], v[82:83] op_sel_hi:[1,0]
	v_pk_mul_f32 v[20:21], v[20:21], v[82:83] op_sel_hi:[1,0]
	v_pk_mul_f32 v[18:19], v[18:19], v[82:83] op_sel_hi:[1,0]
	v_pk_mul_f32 v[16:17], v[16:17], v[82:83] op_sel_hi:[1,0]
	v_pk_mul_f32 v[14:15], v[14:15], v[82:83] op_sel_hi:[1,0]
	v_pk_mul_f32 v[12:13], v[12:13], v[82:83] op_sel_hi:[1,0]
	v_pk_mul_f32 v[10:11], v[10:11], v[82:83] op_sel_hi:[1,0]
	v_pk_mul_f32 v[8:9], v[8:9], v[82:83] op_sel_hi:[1,0]
	v_pk_mul_f32 v[6:7], v[6:7], v[82:83] op_sel_hi:[1,0]
	v_pk_mul_f32 v[4:5], v[4:5], v[82:83] op_sel_hi:[1,0]
	v_pk_mul_f32 v[2:3], v[2:3], v[82:83] op_sel_hi:[1,0]
	v_pk_mul_f32 v[0:1], v[0:1], v[82:83] op_sel_hi:[1,0]
	v_mov_b32_e32 v81, v80
	v_mov_b32_e32 v82, v80
	v_mov_b32_e32 v83, v80
	v_mov_b32_e32 v84, v80
	v_mov_b32_e32 v85, v80
	v_mov_b32_e32 v86, v80
	v_mov_b32_e32 v87, v80
	v_mov_b32_e32 v88, v80
	v_mov_b32_e32 v89, v80
	v_mov_b32_e32 v90, v80
	v_mov_b32_e32 v91, v80
	v_mov_b32_e32 v92, v80
	v_mov_b32_e32 v93, v80
	v_mov_b32_e32 v94, v80
	v_mov_b32_e32 v95, v80
	v_mov_b32_e32 v64, v80
	v_mov_b32_e32 v166, v80
	v_mov_b32_e32 v168, v80
	v_mov_b32_e32 v169, v80
	v_mov_b32_e32 v170, v80
	v_mov_b32_e32 v171, v80
	v_mov_b32_e32 v172, v80
	v_mov_b32_e32 v180, v80
	v_mov_b32_e32 v182, v80
	v_mov_b32_e32 v183, v80
; #define MFMA(a, b, c) __builtin_amdgcn_mfma_f32_32x32x16_bf16((a), (b), (c), 0, 0, 0)
; DI s16x4 vtr(const char* p) { return __builtin_bit_cast(s16x4, __builtin_amdgcn_ds_read_tr16_b64_v4i16((__attribute__((address_space(3))) v4i16_t*)(lds_cptr)p)); }
; DI bf16x8 cat8(s16x4 lo, s16x4 hi) { return __builtin_shufflevector(lo, hi, 0, 1, 2, 3, 4, 5, 6, 7); }
; DI float fexp2(float x) { return __builtin_amdgcn_exp2f(x); }
; template <int DV>
; DI void attn_core(const u16* __restrict__ P, size_t tokbase, int kcol, int vcol, int n1, int n2, int xs0,
;                   bool win, int tq, float m0, float l0, f32x16 (&o)[DV / 32], float& lsum, char* lds) {
;     ...
;       for (int reg = 0; reg < 16; ++reg) { const float e = fexp2(pt[reg]); pt[reg] = e; la += e; }
;       l += la;
; #pragma unroll
;       for (int s2 = 0; s2 < 2; ++s2) {
;         const bf16x8 pb = pack8(pt, s2);
;         const int s16 = 2 * ks + s2;
; #pragma unroll
;         for (int b = 0; b < DV / 32; ++b) {
;           const char* va = base + KB + b * 4096 + s16 * 1024 + trofs;
;           const bf16x8 vf = cat8(vtr(va), vtr(va + 512));
;           o[b] = MFMA(vf, pb, o[b]);
;         }
;       }
;     ...
;       A_STORE(kA, vA, 1);
;       __syncthreads();
;       if (it + 2 < ntiles) A_LOAD(kA, vA, it + 2);
.LBB0_362:
	v_exp_f32_e32 v96, v96
	v_exp_f32_e32 v97, v97
	v_exp_f32_e32 v98, v98
	v_exp_f32_e32 v99, v99
	v_exp_f32_e32 v100, v100
	v_exp_f32_e32 v101, v101
	v_exp_f32_e32 v102, v102
	v_exp_f32_e32 v103, v103
	ds_read_b64_tr_b16 v[216:217], v159 offset:10240
	ds_read_b64_tr_b16 v[218:219], v159 offset:10752
	v_cvt_pk_bf16_f32 v206, v96, v97
	v_cvt_pk_bf16_f32 v207, v98, v99
	v_cvt_pk_bf16_f32 v208, v100, v101
	v_cvt_pk_bf16_f32 v209, v102, v103
	v_exp_f32_e32 v104, v104
	v_exp_f32_e32 v105, v105
	s_waitcnt lgkmcnt(0)
	v_mfma_f32_32x32x16_bf16 v[48:63], v[216:219], v[206:209], v[48:63]
	ds_read_b64_tr_b16 v[216:217], v159 offset:14336
	ds_read_b64_tr_b16 v[218:219], v159 offset:14848
	v_exp_f32_e32 v106, v106
	v_exp_f32_e32 v107, v107
	v_exp_f32_e32 v108, v108
	v_exp_f32_e32 v109, v109
	v_exp_f32_e32 v110, v110
	v_exp_f32_e32 v111, v111
	s_waitcnt lgkmcnt(0)
	v_mfma_f32_32x32x16_bf16 v[32:47], v[216:219], v[206:209], v[32:47]
	ds_read_b64_tr_b16 v[216:217], v159 offset:18432
	ds_read_b64_tr_b16 v[218:219], v159 offset:18944
	s_cmpk_lt_u32 s67, 0x42
	s_cselect_b64 s[36:37], -1, 0
	s_cmpk_gt_u32 s67, 0x41
	s_cselect_b64 s[0:1], -1, 0
	v_add_u32_e32 v185, v154, v147
	s_and_b64 vcc, exec, s[0:1]
	s_waitcnt lgkmcnt(0)
	v_mfma_f32_32x32x16_bf16 v[16:31], v[216:219], v[206:209], v[16:31]
	ds_read_b64_tr_b16 v[216:217], v159 offset:22528
	ds_read_b64_tr_b16 v[218:219], v159 offset:23040
	s_waitcnt lgkmcnt(0)
	v_mfma_f32_32x32x16_bf16 v[0:15], v[216:219], v[206:209], v[0:15]
	ds_read_b64_tr_b16 v[216:217], v159 offset:11264
	ds_read_b64_tr_b16 v[218:219], v159 offset:11776
	v_cvt_pk_bf16_f32 v206, v104, v105
	v_cvt_pk_bf16_f32 v207, v106, v107
	v_cvt_pk_bf16_f32 v208, v108, v109
	v_cvt_pk_bf16_f32 v209, v110, v111
	s_waitcnt lgkmcnt(0)
	s_nop 0
	v_mfma_f32_32x32x16_bf16 v[48:63], v[216:219], v[206:209], v[48:63]
	ds_read_b64_tr_b16 v[216:217], v159 offset:15360
	ds_read_b64_tr_b16 v[218:219], v159 offset:15872
	s_waitcnt lgkmcnt(0)
	v_mfma_f32_32x32x16_bf16 v[32:47], v[216:219], v[206:209], v[32:47]
	ds_read_b64_tr_b16 v[216:217], v159 offset:19456
	ds_read_b64_tr_b16 v[218:219], v159 offset:19968
	s_waitcnt lgkmcnt(0)
	v_mfma_f32_32x32x16_bf16 v[16:31], v[216:219], v[206:209], v[16:31]
	ds_read_b64_tr_b16 v[216:217], v159 offset:23552
	ds_read_b64_tr_b16 v[218:219], v159 offset:24064
	s_waitcnt vmcnt(5)
	ds_write_b128 v158, v[66:69] offset:24576
	s_waitcnt vmcnt(2)
	ds_write_b128 v160, v[70:73] offset:24576
	ds_write_b128 v185, v[74:77] offset:32768
	ds_write_b128 v185, v[128:131] offset:33792
	s_waitcnt vmcnt(1)
	ds_write_b128 v185, v[132:135] offset:34816
	s_waitcnt vmcnt(0)
	ds_write_b128 v185, v[136:139] offset:35840
	s_waitcnt lgkmcnt(0)
	s_barrier
	v_mfma_f32_32x32x16_bf16 v[0:15], v[216:219], v[206:209], v[0:15]
	s_cbranch_vccnz .LBB0_364
	s_add_u32 s94, s94, 0xb9000
	s_addc_u32 s95, s95, 0
	global_load_dwordx4 v[66:69], v174, s[94:95]
	global_load_dwordx4 v[70:73], v175, s[94:95]
	global_load_dwordx4 v[74:77], v176, s[94:95]
	global_load_dwordx4 v[128:131], v177, s[94:95]
	global_load_dwordx4 v[132:135], v178, s[94:95]
	global_load_dwordx4 v[136:139], v179, s[94:95]
; #define MFMA(a, b, c) __builtin_amdgcn_mfma_f32_32x32x16_bf16((a), (b), (c), 0, 0, 0)
; DI int crow(int reg, int h) { return (reg & 3) + 8 * (reg >> 2) + 4 * h; }
; DI float fexp2(float x) { return __builtin_amdgcn_exp2f(x); }
; DI float mx2(float a, float b) { return __builtin_elementwise_maximum(a, b); }
; DI float hmax(float v) { auto rr = __builtin_amdgcn_permlane32_swap(__float_as_uint(v), __float_as_uint(v), false, false); return mx2(__uint_as_float(rr[0]), __uint_as_float(rr[1])); }
; template <int DV>
; DI void attn_core(const u16* __restrict__ P, size_t tokbase, int kcol, int vcol, int n1, int n2, int xs0,
;                   bool win, int tq, float m0, float l0, f32x16 (&o)[DV / 32], float& lsum, char* lds) {
;     ...
;     for (int ks = 0; ks < 2; ++ks) {
;       f32x16 pt = negm;
; #pragma unroll
;       for (int s = 0; s < 4; ++s) {
;         const int ch = 2 * s + h, key = 32 * ks + r;
;         const bf16x8 kf = *(const bf16x8*)(base + ch * 1024 + ((key ^ ch) * 16));
;         const bf16x8 qf = qreg[s];
;         pt = MFMA(kf, qf, pt);
;       }
;       if (domask) {
; #pragma unroll
;         for (int reg = 0; reg < 16; ++reg) {
;           const int d = tq - (kt0 + 32 * ks + crow(reg, h));
;           if (d > 128 || d < -128) pt[reg] = -1e30f;
;         }
;       }
;       float mloc = mx2(pt[0], pt[1]);
; #pragma unroll
;       for (int reg = 2; reg < 16; reg += 2) mloc = mx2(mx2(mloc, pt[reg]), pt[reg + 1]);
;       mloc = hmax(mloc);
;       const bool first = autoinit && it == 0 && ks == 0;
;       if (first || __builtin_amdgcn_ballot_w64(mloc > THR) != 0) {
;         const float d = first ? mloc : fmaxf(mloc, 0.f);
;         const float alpha = fexp2(-d);
;         m += d; l *= alpha;
; #pragma unroll
;         for (int reg = 0; reg < 16; ++reg) { negm[reg] = -m; pt[reg] -= d; }
; #pragma unroll
;         for (int b = 0; b < DV / 32; ++b)
; #pragma unroll
;           for (int reg = 0; reg < 16; ++reg) o[b][reg] *= alpha;
;       }
;       float la = 0.f;
; #pragma unroll
;       for (int reg = 0; reg < 16; ++reg) { const float e = fexp2(pt[reg]); pt[reg] = e; la += e; }
;       l += la;
.LBB0_364:
	v_add_f32_e32 v78, 0, v96
	v_add_f32_e32 v78, v97, v78
	v_add_f32_e32 v78, v98, v78
	v_add_f32_e32 v78, v99, v78
	v_add_f32_e32 v78, v100, v78
	v_add_f32_e32 v78, v101, v78
	v_add_f32_e32 v78, v102, v78
	v_add_f32_e32 v78, v103, v78
	v_add_f32_e32 v78, v104, v78
	v_add_f32_e32 v78, v105, v78
	v_add_f32_e32 v78, v106, v78
	v_add_f32_e32 v78, v107, v78
	v_add_f32_e32 v78, v108, v78
	v_add_f32_e32 v78, v109, v78
	v_add_f32_e32 v78, v110, v78
	v_add_f32_e32 v78, v111, v78
	v_add_f32_e32 v78, v186, v78
	ds_read_b128 v[186:189], v167 offset:24576
	s_waitcnt lgkmcnt(0)
	v_mfma_f32_32x32x16_bf16 v[96:111], v[186:189], v[112:115], v[80:95]
	ds_read_b128 v[186:189], v173 offset:24576
	s_waitcnt lgkmcnt(0)
	v_mfma_f32_32x32x16_bf16 v[96:111], v[186:189], v[116:119], v[96:111]
	ds_read_b128 v[186:189], v181 offset:24576
	s_waitcnt lgkmcnt(0)
	v_mfma_f32_32x32x16_bf16 v[96:111], v[186:189], v[120:123], v[96:111]
	ds_read_b128 v[186:189], v184 offset:24576
	s_waitcnt lgkmcnt(0)
	v_mfma_f32_32x32x16_bf16 v[96:111], v[186:189], v[124:127], v[96:111]
	s_nop 11
	v_maximum3_f32 v79, v96, v97, v97
	v_maximum3_f32 v79, v79, v98, v99
	v_maximum3_f32 v79, v79, v100, v101
	v_maximum3_f32 v79, v79, v102, v103
	v_maximum3_f32 v79, v79, v104, v105
	v_maximum3_f32 v79, v79, v106, v107
	v_maximum3_f32 v79, v79, v108, v109
	v_maximum3_f32 v79, v79, v110, v111
	v_mov_b32_e32 v144, v79
	s_nop 1
	v_permlane32_swap_b32_e32 v79, v144
	v_maximum3_f32 v79, v79, v144, v144
	v_cmp_lt_f32_e32 vcc, s80, v79
	s_cbranch_vccz .LBB0_366
	v_max_f32_e32 v64, v79, v79
	v_max_f32_e32 v64, 0, v64
	v_exp_f32_e64 v82, -v64
	v_add_f32_e32 v165, v165, v64
	v_xor_b32_e32 v80, 0x80000000, v165
	v_pk_add_f32 v[96:97], v[96:97], v[64:65] op_sel_hi:[1,0] neg_lo:[0,1] neg_hi:[0,1]
	v_mul_f32_e32 v78, v78, v82
	v_pk_add_f32 v[98:99], v[98:99], v[64:65] op_sel_hi:[1,0] neg_lo:[0,1] neg_hi:[0,1]
	v_pk_add_f32 v[100:101], v[100:101], v[64:65] op_sel_hi:[1,0] neg_lo:[0,1] neg_hi:[0,1]
	v_pk_add_f32 v[102:103], v[102:103], v[64:65] op_sel_hi:[1,0] neg_lo:[0,1] neg_hi:[0,1]
	v_pk_add_f32 v[104:105], v[104:105], v[64:65] op_sel_hi:[1,0] neg_lo:[0,1] neg_hi:[0,1]
	v_pk_add_f32 v[106:107], v[106:107], v[64:65] op_sel_hi:[1,0] neg_lo:[0,1] neg_hi:[0,1]
	v_pk_add_f32 v[108:109], v[108:109], v[64:65] op_sel_hi:[1,0] neg_lo:[0,1] neg_hi:[0,1]
	v_pk_add_f32 v[110:111], v[110:111], v[64:65] op_sel_hi:[1,0] neg_lo:[0,1] neg_hi:[0,1]
	v_pk_mul_f32 v[62:63], v[62:63], v[82:83] op_sel_hi:[1,0]
	v_pk_mul_f32 v[60:61], v[60:61], v[82:83] op_sel_hi:[1,0]
	v_pk_mul_f32 v[58:59], v[58:59], v[82:83] op_sel_hi:[1,0]
	v_pk_mul_f32 v[56:57], v[56:57], v[82:83] op_sel_hi:[1,0]
	v_pk_mul_f32 v[54:55], v[54:55], v[82:83] op_sel_hi:[1,0]
	v_pk_mul_f32 v[52:53], v[52:53], v[82:83] op_sel_hi:[1,0]
	v_pk_mul_f32 v[50:51], v[50:51], v[82:83] op_sel_hi:[1,0]
	v_pk_mul_f32 v[48:49], v[48:49], v[82:83] op_sel_hi:[1,0]
	v_pk_mul_f32 v[46:47], v[46:47], v[82:83] op_sel_hi:[1,0]
	v_pk_mul_f32 v[44:45], v[44:45], v[82:83] op_sel_hi:[1,0]
	v_pk_mul_f32 v[42:43], v[42:43], v[82:83] op_sel_hi:[1,0]
	v_pk_mul_f32 v[40:41], v[40:41], v[82:83] op_sel_hi:[1,0]
	v_pk_mul_f32 v[38:39], v[38:39], v[82:83] op_sel_hi:[1,0]
	v_pk_mul_f32 v[36:37], v[36:37], v[82:83] op_sel_hi:[1,0]
	v_pk_mul_f32 v[34:35], v[34:35], v[82:83] op_sel_hi:[1,0]
	v_pk_mul_f32 v[32:33], v[32:33], v[82:83] op_sel_hi:[1,0]
	v_pk_mul_f32 v[30:31], v[30:31], v[82:83] op_sel_hi:[1,0]
	v_pk_mul_f32 v[28:29], v[28:29], v[82:83] op_sel_hi:[1,0]
	v_pk_mul_f32 v[26:27], v[26:27], v[82:83] op_sel_hi:[1,0]
	v_pk_mul_f32 v[24:25], v[24:25], v[82:83] op_sel_hi:[1,0]
	v_pk_mul_f32 v[22:23], v[22:23], v[82:83] op_sel_hi:[1,0]
	v_pk_mul_f32 v[20:21], v[20:21], v[82:83] op_sel_hi:[1,0]
	v_pk_mul_f32 v[18:19], v[18:19], v[82:83] op_sel_hi:[1,0]
	v_pk_mul_f32 v[16:17], v[16:17], v[82:83] op_sel_hi:[1,0]
	v_pk_mul_f32 v[14:15], v[14:15], v[82:83] op_sel_hi:[1,0]
	v_pk_mul_f32 v[12:13], v[12:13], v[82:83] op_sel_hi:[1,0]
	v_pk_mul_f32 v[10:11], v[10:11], v[82:83] op_sel_hi:[1,0]
	v_pk_mul_f32 v[8:9], v[8:9], v[82:83] op_sel_hi:[1,0]
	v_pk_mul_f32 v[6:7], v[6:7], v[82:83] op_sel_hi:[1,0]
	v_pk_mul_f32 v[4:5], v[4:5], v[82:83] op_sel_hi:[1,0]
	v_pk_mul_f32 v[2:3], v[2:3], v[82:83] op_sel_hi:[1,0]
	v_pk_mul_f32 v[0:1], v[0:1], v[82:83] op_sel_hi:[1,0]
	v_mov_b32_e32 v81, v80
	v_mov_b32_e32 v82, v80
	v_mov_b32_e32 v83, v80
	v_mov_b32_e32 v84, v80
	v_mov_b32_e32 v85, v80
	v_mov_b32_e32 v86, v80
	v_mov_b32_e32 v87, v80
	v_mov_b32_e32 v88, v80
	v_mov_b32_e32 v89, v80
	v_mov_b32_e32 v90, v80
	v_mov_b32_e32 v91, v80
	v_mov_b32_e32 v92, v80
	v_mov_b32_e32 v93, v80
	v_mov_b32_e32 v94, v80
	v_mov_b32_e32 v95, v80
	v_mov_b32_e32 v64, v80
	v_mov_b32_e32 v166, v80
	v_mov_b32_e32 v168, v80
	v_mov_b32_e32 v169, v80
	v_mov_b32_e32 v170, v80
	v_mov_b32_e32 v171, v80
	v_mov_b32_e32 v172, v80
	v_mov_b32_e32 v180, v80
	v_mov_b32_e32 v182, v80
	v_mov_b32_e32 v183, v80
